# PRE phase: drop the three vmcnt waits at the top of S0 that only stall on the previous item's nt stores (drain once in the preheader)
# baseline (speedup 1.0000x reference)
.LBB0_78:
	s_or_b64 exec, exec, s[38:39]
	v_readlane_b32 s0, v252, 22
	v_readlane_b32 s1, v252, 23
	s_andn2_b64 vcc, exec, s[0:1]
	s_cbranch_vccnz .LBB0_163
	s_ashr_i32 s0, s66, 2
	s_mul_i32 s1, s0, 0xfc00
	s_add_i32 s76, s1, 0
	s_lshl_b32 s1, s0, 8
	s_bfe_u32 s40, s66, 0x10001
	s_and_b32 s41, s66, 1
	s_add_i32 s26, s1, 0
	s_lshl_b32 s43, s40, 5
	s_lshl_b32 s91, s41, 5
	s_add_i32 s38, s76, 0x9000
	s_add_i32 s39, s76, 0xb400
	s_lshl_b32 s50, s0, 6
	s_add_i32 s87, s26, 0x24100
	s_add_u32 s48, s30, 0x6c00000
	s_addc_u32 s49, s31, 0
	s_ashr_i32 s1, s0, 31
	s_lshl_b64 s[24:25], s[0:1], 16
	s_add_u32 s3, s30, s24
	s_addc_u32 s24, s31, s25
	s_add_u32 s54, s3, 0x1b80000
	s_addc_u32 s55, s24, 0
	s_add_u32 s58, s3, 0x1ba0000
	s_addc_u32 s59, s24, 0
	s_lshl_b64 s[24:25], s[0:1], 19
	s_add_u32 s1, s30, s24
	s_addc_u32 s24, s31, s25
	s_lshl_b32 s3, s41, 8
	v_readlane_b32 s25, v252, 24
	s_or_b32 s77, s3, s25
	s_cmp_gt_u32 s66, 3
	s_cselect_b64 s[60:61], -1, 0
	s_lshl_b32 s25, s41, 7
	s_add_i32 s46, s26, s25
	s_add_i32 s47, s46, 0x24a00
	s_add_i32 s46, s46, 0x24c00
	s_lshl_b32 s28, s41, 6
	s_bitcmp1_b32 s66, 1
	s_cselect_b64 s[62:63], -1, 0
	s_lshl_b32 s0, s0, 9
	v_writelane_b32 v255, s96, 9
	s_add_i32 s25, s87, s25
	s_add_i32 s0, s0, 0
	v_writelane_b32 v255, s25, 10
	s_add_i32 s0, s0, 0x24300
	v_writelane_b32 v255, s0, 11
	s_add_i32 s0, s0, s3
	v_writelane_b32 v255, s0, 12
	s_cmp_eq_u32 s41, 0
	v_readlane_b32 s0, v253, 54
	s_cselect_b64 s[26:27], -1, 0
	s_add_u32 s0, s1, s0
	s_addc_u32 s1, s24, 0
	s_add_u32 s0, s0, 0x10400000
	s_addc_u32 s1, s1, 0
	s_cmp_lt_u32 s66, 4
	v_writelane_b32 v255, s0, 13
	s_cselect_b64 s[36:37], -1, 0
	s_waitcnt vmcnt(0)
	v_writelane_b32 v255, s1, 14
	s_and_b64 s[0:1], s[36:37], exec
	v_readlane_b32 s0, v253, 61
	v_readlane_b32 s1, v253, 62
	s_cselect_b32 s29, s0, s1
	s_and_b32 s56, s66, 3
	s_cmp_eq_u32 s56, 0
	s_cselect_b64 s[72:73], -1, 0
	s_cmp_lg_u32 s56, 0
	s_cselect_b64 s[78:79], -1, 0
	s_cmp_eq_u32 s40, 0
	s_cselect_b64 s[24:25], -1, 0
	s_and_b64 s[0:1], s[24:25], exec
	s_cselect_b32 s1, s38, s39
	s_cmp_eq_u32 s40, s41
	s_cselect_b64 s[80:81], -1, 0
	s_lshl_b32 s0, s40, 6
	s_add_i32 s0, s76, s0
	s_and_b64 s[82:83], s[26:27], s[62:63]
	s_bitcmp1_b32 s66, 0
	s_cselect_b64 s[38:39], -1, 0
	s_and_b64 s[84:85], s[24:25], s[38:39]
	s_add_u32 s24, s30, 0xbc00000
	s_addc_u32 s25, s31, 0
	v_writelane_b32 v255, s24, 15
	s_brev_b32 s30, s56
	s_lshr_b32 s30, s30, 25
	v_writelane_b32 v255, s25, 16
	s_lshl_b32 s24, s40, 11
	s_lshl_b32 s25, s41, 10
	s_or_b32 s66, s24, s25
	v_readlane_b32 s24, v252, 25
	s_or_b32 s67, s77, 64
	s_or_b32 s94, s77, 0x80
	s_or_b32 s95, s77, 0xc0
	s_add_i32 s24, s50, s24
	s_or_b32 s25, s66, 0x200
	v_writelane_b32 v255, s30, 17
	s_xor_b64 s[96:97], s[26:27], -1
	v_readlane_b32 s26, v253, 51
	v_readlane_b32 s50, v252, 20
	s_branch .LBB0_81

.LBB0_81:
	v_mov_b32_e32 v1, v180
	v_mov_b32_e32 v48, v180
	v_add_u32_e32 v2, s77, v1
	v_ashrrev_i32_e32 v3, 31, v2
	v_lshlrev_b64 v[2:3], 4, v[2:3]
	v_lshl_add_u64 v[20:21], s[54:55], 0, v[2:3]
	v_lshl_add_u64 v[2:3], s[58:59], 0, v[2:3]
	global_load_dwordx4 v[20:23], v[20:21], off
	s_nop 0
	global_load_dwordx4 v[24:27], v[2:3], off
	v_add_u32_e32 v2, s67, v1
	v_ashrrev_i32_e32 v3, 31, v2
	v_lshlrev_b64 v[2:3], 4, v[2:3]
	v_lshl_add_u64 v[28:29], s[54:55], 0, v[2:3]
	v_lshl_add_u64 v[2:3], s[58:59], 0, v[2:3]
	global_load_dwordx4 v[60:63], v[28:29], off
	global_load_dwordx4 v[56:59], v[2:3], off
	v_add_u32_e32 v2, s94, v1
	v_ashrrev_i32_e32 v3, 31, v2
	v_lshlrev_b64 v[2:3], 4, v[2:3]
	v_lshl_add_u64 v[28:29], s[54:55], 0, v[2:3]
	v_lshl_add_u64 v[2:3], s[58:59], 0, v[2:3]
	global_load_dwordx4 v[72:75], v[28:29], off
	global_load_dwordx4 v[64:67], v[2:3], off
	v_add_u32_e32 v2, s95, v1
	v_ashrrev_i32_e32 v3, 31, v2
	v_lshlrev_b64 v[2:3], 4, v[2:3]
	v_lshl_add_u64 v[28:29], s[54:55], 0, v[2:3]
	v_lshl_add_u64 v[2:3], s[58:59], 0, v[2:3]
	global_load_dwordx4 v[68:71], v[28:29], off
	global_load_dwordx4 v[52:55], v[2:3], off
	s_nop 0
	v_lshlrev_b32_e32 v45, 16, v104
	v_and_b32_e32 v49, 7, v48
	v_lshlrev_b32_e32 v50, 5, v49
	v_add_u32_e32 v51, 0, v50
	v_add_u32_e32 v2, 0x25400, v51
	v_add_u32_e32 v3, 0x25600, v51
	ds_read_b128 v[28:31], v2
	ds_read_b128 v[32:35], v2 offset:16
	ds_read_b128 v[36:39], v3
	ds_read_b128 v[40:43], v3 offset:16
	v_lshlrev_b32_e32 v2, 16, v100
	v_lshlrev_b32_e32 v44, 16, v108
	v_pk_add_f32 v[44:45], v[44:45], v[2:3] op_sel_hi:[1,0] neg_lo:[0,1] neg_hi:[0,1]
	s_waitcnt lgkmcnt(3)
	v_mov_b32_e32 v46, v28
	s_waitcnt lgkmcnt(1)
	v_mov_b32_e32 v47, v36
	v_pk_mul_f32 v[44:45], v[44:45], v[46:47]
	v_mov_b32_e32 v36, v29
	v_add_f32_e32 v2, v44, v2
	v_add_f32_e32 v3, v2, v45
	v_and_b32_e32 v2, 0xffff0000, v100
	v_and_b32_e32 v45, 0xffff0000, v104
	v_and_b32_e32 v44, 0xffff0000, v108
	v_pk_add_f32 v[44:45], v[44:45], v[2:3] op_sel_hi:[1,0] neg_lo:[0,1] neg_hi:[0,1]
	v_add_u32_e32 v1, s42, v48
	v_pk_mul_f32 v[28:29], v[44:45], v[36:37]
	v_mov_b32_e32 v36, v30
	v_add_f32_e32 v2, v28, v2
	v_add_f32_e32 v44, v2, v29
	v_lshlrev_b32_e32 v2, 16, v101
	v_lshlrev_b32_e32 v29, 16, v105
	v_lshlrev_b32_e32 v28, 16, v109
	v_pk_add_f32 v[28:29], v[28:29], v[2:3] op_sel_hi:[1,0] neg_lo:[0,1] neg_hi:[0,1]
	v_mov_b32_e32 v37, v38
	v_pk_mul_f32 v[28:29], v[28:29], v[36:37]
	v_mov_b32_e32 v38, v31
	v_add_f32_e32 v2, v28, v2
	v_add_f32_e32 v36, v2, v29
	v_and_b32_e32 v2, 0xffff0000, v101
	v_and_b32_e32 v29, 0xffff0000, v105
	v_and_b32_e32 v28, 0xffff0000, v109
	v_pk_add_f32 v[28:29], v[28:29], v[2:3] op_sel_hi:[1,0] neg_lo:[0,1] neg_hi:[0,1]
	v_mov_b32_e32 v30, v32
	v_pk_mul_f32 v[28:29], v[28:29], v[38:39]
	s_waitcnt lgkmcnt(0)
	v_mov_b32_e32 v31, v40
	v_add_f32_e32 v2, v28, v2
	v_add_f32_e32 v37, v2, v29
	v_lshlrev_b32_e32 v2, 16, v102
	v_lshlrev_b32_e32 v29, 16, v106
	v_lshlrev_b32_e32 v28, 16, v110
	v_pk_add_f32 v[28:29], v[28:29], v[2:3] op_sel_hi:[1,0] neg_lo:[0,1] neg_hi:[0,1]
	v_mov_b32_e32 v40, v33
	v_pk_mul_f32 v[28:29], v[28:29], v[30:31]
	v_mov_b32_e32 v30, v34
	v_add_f32_e32 v2, v28, v2
	v_add_f32_e32 v32, v2, v29
	v_and_b32_e32 v2, 0xffff0000, v102
	v_and_b32_e32 v29, 0xffff0000, v106
	v_and_b32_e32 v28, 0xffff0000, v110
	v_pk_add_f32 v[28:29], v[28:29], v[2:3] op_sel_hi:[1,0] neg_lo:[0,1] neg_hi:[0,1]
	v_mov_b32_e32 v31, v42
	v_pk_mul_f32 v[28:29], v[28:29], v[40:41]
	v_mov_b32_e32 v42, v35
	v_add_f32_e32 v2, v28, v2
	v_add_f32_e32 v33, v2, v29
	v_lshlrev_b32_e32 v2, 16, v103
	v_lshlrev_b32_e32 v29, 16, v107
	v_lshlrev_b32_e32 v28, 16, v111
	v_pk_add_f32 v[28:29], v[28:29], v[2:3] op_sel_hi:[1,0] neg_lo:[0,1] neg_hi:[0,1]
	v_ashrrev_i32_e32 v1, 3, v1
	v_pk_mul_f32 v[28:29], v[28:29], v[30:31]
	v_add_f32_e32 v30, v44, v44
	v_add_f32_e32 v2, v28, v2
	v_add_f32_e32 v34, v2, v29
	v_and_b32_e32 v2, 0xffff0000, v103
	v_and_b32_e32 v29, 0xffff0000, v107
	v_and_b32_e32 v28, 0xffff0000, v111
	v_pk_add_f32 v[28:29], v[28:29], v[2:3] op_sel_hi:[1,0] neg_lo:[0,1] neg_hi:[0,1]
	v_add_f32_e32 v3, v3, v3
	v_mul_f32_e32 v3, 0x3fb8aa3b, v3
	v_exp_f32_e32 v3, v3
	v_mul_f32_e32 v30, 0x3fb8aa3b, v30
	v_exp_f32_e32 v31, v30
	v_pk_mul_f32 v[28:29], v[28:29], v[42:43]
	v_add_f32_e32 v3, 1.0, v3
	v_rcp_f32_e32 v30, v3
	v_add_f32_e32 v3, 1.0, v31
	v_rcp_f32_e32 v31, v3
	v_add_f32_e32 v2, v28, v2
	v_add_f32_e32 v28, v36, v36
	v_mul_f32_e32 v28, 0x3fb8aa3b, v28
	v_add_f32_e32 v29, v2, v29
	v_pk_fma_f32 v[2:3], v[30:31], 2.0, 1.0 op_sel_hi:[1,0,0] neg_lo:[1,0,0] neg_hi:[1,0,0]
	v_exp_f32_e32 v30, v28
	v_add_f32_e32 v28, v37, v37
	v_mul_f32_e32 v28, 0x3fb8aa3b, v28
	v_exp_f32_e32 v31, v28
	v_cvt_pk_bf16_f32 v28, v2, v3
	v_add_f32_e32 v2, 1.0, v30
	v_add_f32_e32 v30, v32, v32
	v_add_f32_e32 v3, 1.0, v31
	v_add_f32_e32 v31, v33, v33
	v_mul_f32_e32 v30, 0x3fb8aa3b, v30
	v_mul_f32_e32 v31, 0x3fb8aa3b, v31
	v_add_f32_e32 v32, v34, v34
	v_add_f32_e32 v29, v29, v29
	v_exp_f32_e32 v30, v30
	v_exp_f32_e32 v31, v31
	v_mul_f32_e32 v32, 0x3fb8aa3b, v32
	v_mul_f32_e32 v29, 0x3fb8aa3b, v29
	v_exp_f32_e32 v32, v32
	v_exp_f32_e32 v29, v29
	v_rcp_f32_e32 v2, v2
	v_rcp_f32_e32 v3, v3
	v_add_f32_e32 v30, 1.0, v30
	v_add_f32_e32 v31, 1.0, v31
	v_rcp_f32_e32 v30, v30
	v_rcp_f32_e32 v31, v31
	v_add_f32_e32 v32, 1.0, v32
	v_add_f32_e32 v29, 1.0, v29
	v_rcp_f32_e32 v32, v32
	v_rcp_f32_e32 v33, v29
	v_pk_fma_f32 v[2:3], v[2:3], 2.0, 1.0 op_sel_hi:[1,0,0] neg_lo:[1,0,0] neg_hi:[1,0,0]
	v_mul_lo_u32 v76, v1, s64
	v_cvt_pk_bf16_f32 v29, v2, v3
	v_pk_fma_f32 v[2:3], v[30:31], 2.0, 1.0 op_sel_hi:[1,0,0] neg_lo:[1,0,0] neg_hi:[1,0,0]
	v_lshlrev_b32_e32 v77, 4, v49
	v_cvt_pk_bf16_f32 v30, v2, v3
	v_pk_fma_f32 v[2:3], v[32:33], 2.0, 1.0 op_sel_hi:[1,0,0] neg_lo:[1,0,0] neg_hi:[1,0,0]
	v_readlane_b32 s27, v253, 61
	v_cvt_pk_bf16_f32 v31, v2, v3
	v_add_u32_e32 v3, 0x25700, v51
	v_add3_u32 v2, s27, v76, v77
	ds_write_b128 v2, v[28:31]
	v_add_u32_e32 v2, 0x25500, v51
	ds_read_b128 v[28:31], v2
	ds_read_b128 v[32:35], v2 offset:16
	ds_read_b128 v[36:39], v3
	ds_read_b128 v[40:43], v3 offset:16
	s_nop 0
	v_lshlrev_b32_e32 v2, 16, v112
	v_and_b32_e32 v3, 0xffff0000, v112
	v_lshlrev_b32_e32 v44, 16, v116
	v_and_b32_e32 v45, 0xffff0000, v116
	v_lshlrev_b32_e32 v46, 16, v120
	v_and_b32_e32 v47, 0xffff0000, v120
	v_pk_add_f32 v[44:45], v[44:45], v[2:3] neg_lo:[0,1] neg_hi:[0,1]
	v_readlane_b32 s27, v253, 62
	s_waitcnt lgkmcnt(3)
	v_pk_fma_f32 v[28:29], v[44:45], v[28:29], v[2:3]
	v_pk_add_f32 v[2:3], v[46:47], v[2:3] neg_lo:[0,1] neg_hi:[0,1]
	v_lshlrev_b32_e32 v44, 16, v121
	s_waitcnt lgkmcnt(1)
	v_pk_fma_f32 v[2:3], v[2:3], v[36:37], v[28:29]
	v_lshlrev_b32_e32 v28, 16, v113
	v_and_b32_e32 v29, 0xffff0000, v113
	v_lshlrev_b32_e32 v36, 16, v117
	v_and_b32_e32 v37, 0xffff0000, v117
	v_and_b32_e32 v45, 0xffff0000, v121
	v_pk_add_f32 v[36:37], v[36:37], v[28:29] neg_lo:[0,1] neg_hi:[0,1]
	s_nop 0
	v_lshlrev_b32_e32 v46, 16, v144
	v_pk_fma_f32 v[30:31], v[36:37], v[30:31], v[28:29]
	v_pk_add_f32 v[28:29], v[44:45], v[28:29] neg_lo:[0,1] neg_hi:[0,1]
	v_lshlrev_b32_e32 v36, 16, v118
	v_pk_fma_f32 v[30:31], v[28:29], v[38:39], v[30:31]
	v_lshlrev_b32_e32 v28, 16, v114
	v_and_b32_e32 v29, 0xffff0000, v114
	v_and_b32_e32 v37, 0xffff0000, v118
	v_lshlrev_b32_e32 v38, 16, v122
	v_and_b32_e32 v39, 0xffff0000, v122
	v_pk_add_f32 v[36:37], v[36:37], v[28:29] neg_lo:[0,1] neg_hi:[0,1]
	v_lshlrev_b32_e32 v44, 16, v140
	v_pk_fma_f32 v[32:33], v[36:37], v[32:33], v[28:29]
	v_pk_add_f32 v[28:29], v[38:39], v[28:29] neg_lo:[0,1] neg_hi:[0,1]
	v_lshlrev_b32_e32 v36, 16, v119
	v_and_b32_e32 v37, 0xffff0000, v119
	v_lshlrev_b32_e32 v38, 16, v115
	v_and_b32_e32 v39, 0xffff0000, v115
	s_waitcnt lgkmcnt(0)
	v_pk_fma_f32 v[32:33], v[28:29], v[40:41], v[32:33]
	v_lshlrev_b32_e32 v28, 16, v123
	v_and_b32_e32 v29, 0xffff0000, v123
	v_pk_add_f32 v[36:37], v[36:37], v[38:39] neg_lo:[0,1] neg_hi:[0,1]
	v_pk_add_f32 v[28:29], v[28:29], v[38:39] neg_lo:[0,1] neg_hi:[0,1]
	v_pk_fma_f32 v[34:35], v[36:37], v[34:35], v[38:39]
	v_and_b32_e32 v45, 0xffff0000, v140
	v_pk_fma_f32 v[34:35], v[28:29], v[42:43], v[34:35]
	v_cvt_pk_bf16_f32 v28, v2, v3
	v_cvt_pk_bf16_f32 v29, v30, v31
	v_cvt_pk_bf16_f32 v30, v32, v33
	v_cvt_pk_bf16_f32 v31, v34, v35
	v_add3_u32 v2, s27, v76, v77
	ds_write_b128 v2, v[28:31]
	v_add_u32_e32 v2, 0x24e00, v51
	v_add_u32_e32 v3, 0x24f00, v51
	ds_read_b128 v[28:31], v2
	ds_read_b128 v[32:35], v2 offset:16
	ds_read_b128 v[36:39], v3
	ds_read_b128 v[40:43], v3 offset:16
	v_lshlrev_b32_e32 v2, 16, v136
	v_and_b32_e32 v3, 0xffff0000, v136
	v_and_b32_e32 v47, 0xffff0000, v144
	v_pk_add_f32 v[44:45], v[44:45], v[2:3] neg_lo:[0,1] neg_hi:[0,1]
	v_cmp_gt_i32_e32 vcc, 32, v1
	s_waitcnt lgkmcnt(3)
	v_pk_fma_f32 v[28:29], v[44:45], v[28:29], v[2:3]
	v_pk_add_f32 v[2:3], v[46:47], v[2:3] neg_lo:[0,1] neg_hi:[0,1]
	v_lshlrev_b32_e32 v44, 16, v145
	s_waitcnt lgkmcnt(1)
	v_pk_fma_f32 v[28:29], v[2:3], v[36:37], v[28:29]
	v_lshlrev_b32_e32 v2, 16, v137
	v_and_b32_e32 v3, 0xffff0000, v137
	v_lshlrev_b32_e32 v36, 16, v141
	v_and_b32_e32 v37, 0xffff0000, v141
	v_and_b32_e32 v45, 0xffff0000, v145
	v_pk_add_f32 v[36:37], v[36:37], v[2:3] neg_lo:[0,1] neg_hi:[0,1]
	v_lshlrev_b32_e32 v46, 16, v132
	v_pk_fma_f32 v[30:31], v[36:37], v[30:31], v[2:3]
	v_pk_add_f32 v[2:3], v[44:45], v[2:3] neg_lo:[0,1] neg_hi:[0,1]
	v_lshlrev_b32_e32 v36, 16, v142
	v_pk_fma_f32 v[30:31], v[2:3], v[38:39], v[30:31]
	v_lshlrev_b32_e32 v2, 16, v138
	v_and_b32_e32 v3, 0xffff0000, v138
	v_and_b32_e32 v37, 0xffff0000, v142
	v_lshlrev_b32_e32 v38, 16, v146
	v_and_b32_e32 v39, 0xffff0000, v146
	v_pk_add_f32 v[36:37], v[36:37], v[2:3] neg_lo:[0,1] neg_hi:[0,1]
	v_lshlrev_b32_e32 v44, 16, v128
	v_pk_fma_f32 v[32:33], v[36:37], v[32:33], v[2:3]
	v_pk_add_f32 v[2:3], v[38:39], v[2:3] neg_lo:[0,1] neg_hi:[0,1]
	v_lshlrev_b32_e32 v36, 16, v143
	v_and_b32_e32 v37, 0xffff0000, v143
	v_lshlrev_b32_e32 v38, 16, v139
	v_and_b32_e32 v39, 0xffff0000, v139
	s_waitcnt lgkmcnt(0)
	v_pk_fma_f32 v[32:33], v[2:3], v[40:41], v[32:33]
	v_lshlrev_b32_e32 v2, 16, v147
	v_and_b32_e32 v3, 0xffff0000, v147
	v_pk_add_f32 v[36:37], v[36:37], v[38:39] neg_lo:[0,1] neg_hi:[0,1]
	v_pk_add_f32 v[2:3], v[2:3], v[38:39] neg_lo:[0,1] neg_hi:[0,1]
	v_pk_fma_f32 v[34:35], v[36:37], v[34:35], v[38:39]
	v_and_b32_e32 v45, 0xffff0000, v128
	v_pk_fma_f32 v[34:35], v[2:3], v[42:43], v[34:35]
	v_mov_b32_e32 v2, 0x1d400
	v_mov_b32_e32 v3, 0xd800
	v_cndmask_b32_e32 v2, v2, v3, vcc
	v_lshlrev_b32_e32 v3, 8, v1
	v_add_u32_e32 v2, 0, v2
	v_and_b32_e32 v3, 0x1f00, v3
	v_add3_u32 v2, v2, v3, v50
	ds_write_b128 v2, v[28:31]
	ds_write_b128 v2, v[32:35] offset:16
	v_add_u32_e32 v2, 0x25000, v51
	v_add_u32_e32 v3, 0x25100, v51
	ds_read_b128 v[28:31], v2
	ds_read_b128 v[32:35], v2 offset:16
	ds_read_b128 v[36:39], v3
	ds_read_b128 v[40:43], v3 offset:16
	v_lshlrev_b32_e32 v2, 16, v124
	v_and_b32_e32 v3, 0xffff0000, v124
	v_and_b32_e32 v47, 0xffff0000, v132
	v_pk_add_f32 v[44:45], v[44:45], v[2:3] neg_lo:[0,1] neg_hi:[0,1]
	v_cmp_eq_u32_e32 vcc, 0, v49
	s_waitcnt lgkmcnt(3)
	v_pk_fma_f32 v[28:29], v[44:45], v[28:29], v[2:3]
	v_pk_add_f32 v[2:3], v[46:47], v[2:3] neg_lo:[0,1] neg_hi:[0,1]
	s_waitcnt lgkmcnt(1)
	v_pk_fma_f32 v[76:77], v[2:3], v[36:37], v[28:29]
	v_lshlrev_b32_e32 v2, 16, v125
	v_and_b32_e32 v3, 0xffff0000, v125
	v_lshlrev_b32_e32 v28, 16, v129
	v_and_b32_e32 v29, 0xffff0000, v129
	v_lshlrev_b32_e32 v36, 16, v133
	v_and_b32_e32 v37, 0xffff0000, v133
	v_pk_add_f32 v[28:29], v[28:29], v[2:3] neg_lo:[0,1] neg_hi:[0,1]
	s_nop 0
	v_pk_fma_f32 v[28:29], v[28:29], v[30:31], v[2:3]
	v_pk_add_f32 v[2:3], v[36:37], v[2:3] neg_lo:[0,1] neg_hi:[0,1]
	v_lshlrev_b32_e32 v30, 16, v134
	v_pk_fma_f32 v[78:79], v[2:3], v[38:39], v[28:29]
	v_lshlrev_b32_e32 v2, 16, v126
	v_and_b32_e32 v3, 0xffff0000, v126
	v_lshlrev_b32_e32 v28, 16, v130
	v_and_b32_e32 v29, 0xffff0000, v130
	v_and_b32_e32 v31, 0xffff0000, v134
	v_pk_add_f32 v[28:29], v[28:29], v[2:3] neg_lo:[0,1] neg_hi:[0,1]
	v_add_u32_e32 v38, 0x24700, v51
	v_pk_fma_f32 v[28:29], v[28:29], v[32:33], v[2:3]
	v_pk_add_f32 v[2:3], v[30:31], v[2:3] neg_lo:[0,1] neg_hi:[0,1]
	v_lshlrev_b32_e32 v32, 16, v127
	s_waitcnt lgkmcnt(0)
	v_pk_fma_f32 v[80:81], v[2:3], v[40:41], v[28:29]
	v_lshlrev_b32_e32 v28, 16, v131
	v_and_b32_e32 v29, 0xffff0000, v131
	v_and_b32_e32 v33, 0xffff0000, v127
	v_pk_add_f32 v[36:37], v[28:29], v[32:33] neg_lo:[0,1] neg_hi:[0,1]
	ds_read_b128 v[28:31], v38
	v_lshlrev_b32_e32 v2, 16, v135
	v_and_b32_e32 v3, 0xffff0000, v135
	v_pk_fma_f32 v[34:35], v[36:37], v[34:35], v[32:33]
	v_pk_add_f32 v[2:3], v[2:3], v[32:33] neg_lo:[0,1] neg_hi:[0,1]
	s_nop 0
	v_pk_fma_f32 v[82:83], v[2:3], v[42:43], v[34:35]
	ds_read_b128 v[32:35], v38 offset:16
	s_waitcnt lgkmcnt(1)
	v_mul_f32_e32 v3, v77, v29
	v_mul_f32_e32 v2, v76, v28
	v_mul_f32_e32 v3, v3, v3
	v_fmac_f32_e32 v3, v2, v2
	v_mul_f32_e32 v2, v78, v30
	v_fmac_f32_e32 v3, v2, v2
	v_mul_f32_e32 v2, v79, v31
	v_fmac_f32_e32 v3, v2, v2
	s_waitcnt lgkmcnt(0)
	v_mul_f32_e32 v2, v80, v32
	v_fmac_f32_e32 v3, v2, v2
	v_mul_f32_e32 v2, v81, v33
	v_fmac_f32_e32 v3, v2, v2
	v_mul_f32_e32 v2, v82, v34
	v_fmac_f32_e32 v3, v2, v2
	v_mul_f32_e32 v2, v83, v35
	v_lshlrev_b32_e32 v28, 2, v48
	v_fmac_f32_e32 v3, v2, v2
	v_xor_b32_e32 v2, 4, v28
	ds_bpermute_b32 v2, v2, v3
	s_waitcnt lgkmcnt(0)
	v_add_f32_e32 v2, v3, v2
	v_xor_b32_e32 v3, 8, v28
	ds_bpermute_b32 v3, v3, v2
	s_waitcnt lgkmcnt(0)
	v_add_f32_e32 v2, v2, v3
	v_xor_b32_e32 v3, 16, v28
	ds_bpermute_b32 v3, v3, v2
	s_and_saveexec_b64 s[30:31], vcc
	s_cbranch_execz .LBB0_83
	s_waitcnt lgkmcnt(0)
	v_add_f32_e32 v2, v2, v3
	v_add_f32_e32 v2, 0x2b8cbccc, v2
	s_mov_b32 s27, 0xf800000
	v_mul_f32_e32 v3, 0x4f800000, v2
	v_cmp_gt_f32_e32 vcc, s27, v2
	v_lshl_add_u32 v1, v1, 2, 0
	v_add_u32_e32 v1, 0x24000, v1
	v_cndmask_b32_e32 v2, v2, v3, vcc
	v_sqrt_f32_e32 v3, v2
	s_nop 0
	v_add_u32_e32 v28, -1, v3
	v_fma_f32 v30, -v28, v3, v2
	v_add_u32_e32 v29, 1, v3
	v_cmp_ge_f32_e64 s[38:39], 0, v30
	s_nop 1
	v_cndmask_b32_e64 v28, v3, v28, s[38:39]
	v_fma_f32 v3, -v29, v3, v2
	v_cmp_lt_f32_e64 s[38:39], 0, v3
	s_nop 1
	v_cndmask_b32_e64 v3, v28, v29, s[38:39]
	v_mul_f32_e32 v28, 0x37800000, v3
	v_cndmask_b32_e32 v3, v3, v28, vcc
	v_cmp_class_f32_e32 vcc, v2, v222
	s_nop 1
	v_cndmask_b32_e32 v2, v3, v2, vcc
	v_div_scale_f32 v3, s[38:39], v2, v2, 1.0
	v_rcp_f32_e32 v28, v3
	s_nop 0
	v_fma_f32 v29, -v3, v28, 1.0
	v_fmac_f32_e32 v28, v29, v28
	v_div_scale_f32 v29, vcc, 1.0, v2, 1.0
	v_mul_f32_e32 v30, v29, v28
	v_fma_f32 v31, -v3, v30, v29
	v_fmac_f32_e32 v30, v31, v28
	v_fma_f32 v3, -v3, v30, v29
	v_div_fmas_f32 v3, v3, v28, v30
	v_div_fixup_f32 v2, v3, v2, 1.0
	ds_write_b32 v1, v2
